# P3 per-CU order changed to MLA(long unit) -> MoBA gate units -> MLA(short unit): gate list-append atomics no longer issued by all CUs at once
# speedup vs baseline: 1.0503x; 1.0500x over previous
.LBB0_709:
	s_cmp_lt_i32 s68, 4
	s_cselect_b64 s[4:5], -1, 0
	s_and_b64 s[4:5], s[4:5], s[0:1]
	s_andn2_b64 vcc, exec, s[4:5]
	s_cbranch_vccnz .LBB0_753
	s_mov_b64 s[10:11], s[30:31]
	s_cmpk_gt_i32 s3, 0xff
	s_cbranch_scc1 .LBB0_753
	s_add_u32 s27, s10, 0x40000
	s_addc_u32 s33, s11, 0
	s_add_u32 s35, s10, 0x8000000
	s_addc_u32 s44, s11, 0
	s_add_u32 s45, s10, 0x10000000
	s_addc_u32 s46, s11, 0
	s_add_u32 s47, s10, 0x13000000
	s_addc_u32 s48, s11, 0
	s_add_u32 s49, s10, 0x16000000
	s_addc_u32 s50, s11, 0
	s_add_u32 s51, s10, 0x19000000
	s_addc_u32 s54, s11, 0
	s_add_u32 s55, s10, 0x60000
	v_mbcnt_lo_u32_b32 v2, -1, 0
	s_addc_u32 s56, s11, 0
	v_mbcnt_hi_u32_b32 v210, -1, v2
	s_add_u32 s57, s10, 0xc000000
	v_and_b32_e32 v2, 64, v210
	s_addc_u32 s58, s11, 0
	v_mov_b32_e32 v199, 0
	s_movk_i32 s59, 0x110
	s_mov_b32 s60, 0xff61b1e6
	v_mov_b32_e32 v209, 1
	s_movk_i32 s61, 0x600
	s_movk_i32 s62, 0x90
	s_movk_i32 s63, 0xc00
	s_movk_i32 s64, 0x190
	s_mov_b32 s65, 0xc800
	s_mov_b32 s66, 0x41800000
	v_mov_b32_e32 v211, 0xff61b1e6
	v_xor_b32_e32 v212, 32, v210
	v_add_u32_e32 v213, 64, v2
	v_mov_b32_e32 v214, 0xff800000
	v_writelane_b32 v236, 0, 15
	s_mov_b32 s67, s3
	s_branch .LBB0_713
.LBB0_712:
	v_writelane_b32 v236, 0, 15
	s_add_i32 s67, s67, s97
	s_cmpk_gt_i32 s67, 0xff
	s_cbranch_scc1 .LBB0_753
.LBB0_713:
	s_ashr_i32 s14, s67, 5
	s_lshl_b32 s0, s14, 6
	s_and_b32 s70, s67, 31
	s_ashr_i32 s1, s0, 31
	s_xor_b32 s71, s70, 63
	s_lshl_b64 s[0:1], s[0:1], 2
	s_add_u32 s16, s55, s0
	s_addc_u32 s17, s56, s1
	s_ashr_i32 s15, s14, 31
	s_lshl_b64 s[12:13], s[14:15], 22
	s_add_u32 s20, s57, s12
	s_addc_u32 s21, s58, s13
	s_lshl_b32 s0, s14, 13
	s_ashr_i32 s1, s0, 31
	s_lshl_b64 s[0:1], s[0:1], 1
	s_add_u32 s22, s27, s0
	s_addc_u32 s23, s33, s1
	s_lshl_b32 s0, s14, 7
	s_ashr_i32 s1, s0, 31
	s_lshl_b64 s[18:19], s[0:1], 1
	s_add_u32 s24, s51, s18
	s_addc_u32 s25, s54, s19
	v_readlane_b32 vcc_lo, v236, 15
	s_nop 3
	s_cmp_eq_u32 vcc_lo, 0
	s_cbranch_scc1 .LBB0_724
	s_mov_b64 s[36:37], -1
	s_branch .LBB0_716

.LBB0_724:
	s_mul_i32 s0, s14, 0xc0
	s_ashr_i32 s1, s0, 31
	s_lshl_b64 s[0:1], s[0:1], 1
	s_add_u32 s8, s45, s0
	s_addc_u32 s9, s46, s1
	s_add_u32 s14, s47, s0
	s_addc_u32 s15, s48, s1
	s_add_u32 s16, s49, s12
	s_addc_u32 s17, s50, s13
	s_add_u32 s18, s35, s18
	s_addc_u32 s19, s44, s19
	s_add_u32 s20, s16, 0x200000
	s_addc_u32 s21, s17, 0
	v_readlane_b32 vcc_lo, v236, 15
	s_nop 3
	s_cmp_eq_u32 vcc_lo, 0
	s_cselect_b64 s[6:7], -1, 0
	s_branch .LBB0_726
.LBB0_725:
	v_cmp_lt_i32_e32 vcc, v212, v213
	v_lshlrev_b32_e32 v198, 1, v205
	s_nop 0
	v_cndmask_b32_e32 v66, v210, v212, vcc
	v_lshlrev_b32_e32 v66, 2, v66
	ds_bpermute_b32 v66, v66, v207
	s_barrier
	s_waitcnt lgkmcnt(0)
	v_add_f32_e32 v66, v207, v66
	v_div_scale_f32 v67, s[6:7], v66, v66, 1.0
	v_rcp_f32_e32 v68, v67
	v_div_scale_f32 v69, vcc, 1.0, v66, 1.0
	s_mov_b64 s[6:7], 0
	v_fma_f32 v70, -v67, v68, 1.0
	v_fmac_f32_e32 v68, v70, v68
	v_mul_f32_e32 v70, v69, v68
	v_fma_f32 v71, -v67, v70, v69
	v_fmac_f32_e32 v70, v71, v68
	v_fma_f32 v67, -v67, v70, v69
	v_div_fmas_f32 v67, v67, v68, v70
	v_div_fixup_f32 v66, v67, v66, 1.0
	v_lshlrev_b64 v[68:69], 12, v[200:201]
	v_lshl_add_u64 v[68:69], s[18:19], 0, v[68:69]
	v_pk_mul_f32 v[50:51], v[50:51], v[66:67] op_sel_hi:[1,0]
	v_pk_mul_f32 v[52:53], v[52:53], v[66:67] op_sel_hi:[1,0]
	v_pk_mul_f32 v[34:35], v[34:35], v[66:67] op_sel_hi:[1,0]
	v_pk_mul_f32 v[36:37], v[36:37], v[66:67] op_sel_hi:[1,0]
	v_pk_mul_f32 v[18:19], v[18:19], v[66:67] op_sel_hi:[1,0]
	v_pk_mul_f32 v[20:21], v[20:21], v[66:67] op_sel_hi:[1,0]
	v_pk_mul_f32 v[2:3], v[2:3], v[66:67] op_sel_hi:[1,0]
	v_pk_mul_f32 v[4:5], v[4:5], v[66:67] op_sel_hi:[1,0]
	v_lshl_add_u64 v[68:69], v[68:69], 0, v[198:199]
	v_cvt_pk_bf16_f32 v50, v50, v51
	v_cvt_pk_bf16_f32 v51, v52, v53
	v_cvt_pk_bf16_f32 v34, v34, v35
	v_cvt_pk_bf16_f32 v35, v36, v37
	v_cvt_pk_bf16_f32 v18, v18, v19
	v_cvt_pk_bf16_f32 v19, v20, v21
	v_cvt_pk_bf16_f32 v2, v2, v3
	v_cvt_pk_bf16_f32 v3, v4, v5
	global_store_dwordx2 v[68:69], v[50:51], off
	v_pk_mul_f32 v[50:51], v[54:55], v[66:67] op_sel_hi:[1,0]
	v_pk_mul_f32 v[52:53], v[56:57], v[66:67] op_sel_hi:[1,0]
	global_store_dwordx2 v[68:69], v[34:35], off offset:64
	v_pk_mul_f32 v[34:35], v[38:39], v[66:67] op_sel_hi:[1,0]
	v_pk_mul_f32 v[36:37], v[40:41], v[66:67] op_sel_hi:[1,0]
	global_store_dwordx2 v[68:69], v[18:19], off offset:128
	v_pk_mul_f32 v[18:19], v[22:23], v[66:67] op_sel_hi:[1,0]
	v_pk_mul_f32 v[20:21], v[24:25], v[66:67] op_sel_hi:[1,0]
	global_store_dwordx2 v[68:69], v[2:3], off offset:192
	v_pk_mul_f32 v[2:3], v[6:7], v[66:67] op_sel_hi:[1,0]
	v_pk_mul_f32 v[4:5], v[8:9], v[66:67] op_sel_hi:[1,0]
	v_cvt_pk_bf16_f32 v50, v50, v51
	v_cvt_pk_bf16_f32 v51, v52, v53
	v_cvt_pk_bf16_f32 v34, v34, v35
	v_cvt_pk_bf16_f32 v35, v36, v37
	v_cvt_pk_bf16_f32 v18, v18, v19
	v_cvt_pk_bf16_f32 v19, v20, v21
	v_cvt_pk_bf16_f32 v2, v2, v3
	v_cvt_pk_bf16_f32 v3, v4, v5
	global_store_dwordx2 v[68:69], v[50:51], off offset:16
	v_pk_mul_f32 v[50:51], v[58:59], v[66:67] op_sel_hi:[1,0]
	v_pk_mul_f32 v[52:53], v[60:61], v[66:67] op_sel_hi:[1,0]
	global_store_dwordx2 v[68:69], v[34:35], off offset:80
	v_pk_mul_f32 v[34:35], v[42:43], v[66:67] op_sel_hi:[1,0]
	v_pk_mul_f32 v[36:37], v[44:45], v[66:67] op_sel_hi:[1,0]
	global_store_dwordx2 v[68:69], v[18:19], off offset:144
	v_pk_mul_f32 v[18:19], v[26:27], v[66:67] op_sel_hi:[1,0]
	v_pk_mul_f32 v[20:21], v[28:29], v[66:67] op_sel_hi:[1,0]
	global_store_dwordx2 v[68:69], v[2:3], off offset:208
	v_pk_mul_f32 v[2:3], v[10:11], v[66:67] op_sel_hi:[1,0]
	v_pk_mul_f32 v[4:5], v[12:13], v[66:67] op_sel_hi:[1,0]
	v_cvt_pk_bf16_f32 v50, v50, v51
	v_cvt_pk_bf16_f32 v51, v52, v53
	v_cvt_pk_bf16_f32 v34, v34, v35
	v_cvt_pk_bf16_f32 v35, v36, v37
	v_cvt_pk_bf16_f32 v18, v18, v19
	v_cvt_pk_bf16_f32 v19, v20, v21
	v_cvt_pk_bf16_f32 v2, v2, v3
	v_cvt_pk_bf16_f32 v3, v4, v5
	global_store_dwordx2 v[68:69], v[50:51], off offset:32
	v_pk_mul_f32 v[50:51], v[62:63], v[66:67] op_sel_hi:[1,0]
	v_pk_mul_f32 v[52:53], v[64:65], v[66:67] op_sel_hi:[1,0]
	global_store_dwordx2 v[68:69], v[34:35], off offset:96
	v_pk_mul_f32 v[34:35], v[46:47], v[66:67] op_sel_hi:[1,0]
	v_pk_mul_f32 v[36:37], v[48:49], v[66:67] op_sel_hi:[1,0]
	global_store_dwordx2 v[68:69], v[18:19], off offset:160
	v_pk_mul_f32 v[18:19], v[30:31], v[66:67] op_sel_hi:[1,0]
	v_pk_mul_f32 v[20:21], v[32:33], v[66:67] op_sel_hi:[1,0]
	global_store_dwordx2 v[68:69], v[2:3], off offset:224
	v_pk_mul_f32 v[2:3], v[14:15], v[66:67] op_sel_hi:[1,0]
	v_pk_mul_f32 v[4:5], v[16:17], v[66:67] op_sel_hi:[1,0]
	v_cvt_pk_bf16_f32 v50, v50, v51
	v_cvt_pk_bf16_f32 v51, v52, v53
	v_cvt_pk_bf16_f32 v34, v34, v35
	v_cvt_pk_bf16_f32 v35, v36, v37
	v_cvt_pk_bf16_f32 v18, v18, v19
	v_cvt_pk_bf16_f32 v19, v20, v21
	v_cvt_pk_bf16_f32 v2, v2, v3
	v_cvt_pk_bf16_f32 v3, v4, v5
	s_and_b64 vcc, exec, s[22:23]
	global_store_dwordx2 v[68:69], v[50:51], off offset:48
	global_store_dwordx2 v[68:69], v[34:35], off offset:112
	global_store_dwordx2 v[68:69], v[18:19], off offset:176
	global_store_dwordx2 v[68:69], v[2:3], off offset:240
	v_readlane_b32 vcc_lo, v236, 15
	s_nop 3
	s_cmp_lg_u32 vcc_lo, 0
	s_cbranch_scc1 .LBB0_712
	v_writelane_b32 v236, 1, 15
	s_branch .LBB0_713

	.amdhsa_kernel _Z3fwd4Args
		.amdhsa_group_segment_fixed_size 0
		.amdhsa_private_segment_fixed_size 0
		.amdhsa_kernarg_size 408
		.amdhsa_user_sgpr_count 2
		.amdhsa_user_sgpr_dispatch_ptr 0
		.amdhsa_user_sgpr_queue_ptr 0
		.amdhsa_user_sgpr_kernarg_segment_ptr 1
		.amdhsa_user_sgpr_dispatch_id 0
		.amdhsa_user_sgpr_kernarg_preload_length 0
		.amdhsa_user_sgpr_kernarg_preload_offset 0
		.amdhsa_user_sgpr_private_segment_size 0
		.amdhsa_uses_dynamic_stack 0
		.amdhsa_enable_private_segment 0
		.amdhsa_system_sgpr_workgroup_id_x 1
		.amdhsa_system_sgpr_workgroup_id_y 0
		.amdhsa_system_sgpr_workgroup_id_z 0
		.amdhsa_system_sgpr_workgroup_info 0
		.amdhsa_system_vgpr_workitem_id 2
		.amdhsa_next_free_vgpr 240
		.amdhsa_next_free_sgpr 98
		.amdhsa_accum_offset 240
		.amdhsa_reserve_vcc 1
		.amdhsa_float_round_mode_32 0
		.amdhsa_float_round_mode_16_64 0
		.amdhsa_float_denorm_mode_32 3
		.amdhsa_float_denorm_mode_16_64 3
		.amdhsa_dx10_clamp 1
		.amdhsa_ieee_mode 1
		.amdhsa_fp16_overflow 0
		.amdhsa_tg_split 0
		.amdhsa_exception_fp_ieee_invalid_op 0
		.amdhsa_exception_fp_denorm_src 0
		.amdhsa_exception_fp_ieee_div_zero 0
		.amdhsa_exception_fp_ieee_overflow 0
		.amdhsa_exception_fp_ieee_underflow 0
		.amdhsa_exception_fp_ieee_inexact 0
		.amdhsa_exception_int_div_zero 0
	.end_amdhsa_kernel

amdhsa.kernels:
  - .agpr_count:     0
    .args:
      - .offset:         0
        .size:           152
        .value_kind:     by_value
      - .offset:         152
        .size:           4
        .value_kind:     hidden_block_count_x
      - .offset:         156
        .size:           4
        .value_kind:     hidden_block_count_y
      - .offset:         160
        .size:           4
        .value_kind:     hidden_block_count_z
      - .offset:         164
        .size:           2
        .value_kind:     hidden_group_size_x
      - .offset:         166
        .size:           2
        .value_kind:     hidden_group_size_y
      - .offset:         168
        .size:           2
        .value_kind:     hidden_group_size_z
      - .offset:         170
        .size:           2
        .value_kind:     hidden_remainder_x
      - .offset:         172
        .size:           2
        .value_kind:     hidden_remainder_y
      - .offset:         174
        .size:           2
        .value_kind:     hidden_remainder_z
      - .offset:         192
        .size:           8
        .value_kind:     hidden_global_offset_x
      - .offset:         200
        .size:           8
        .value_kind:     hidden_global_offset_y
      - .offset:         208
        .size:           8
        .value_kind:     hidden_global_offset_z
      - .offset:         216
        .size:           2
        .value_kind:     hidden_grid_dims
      - .offset:         240
        .size:           8
        .value_kind:     hidden_multigrid_sync_arg
      - .offset:         272
        .size:           4
        .value_kind:     hidden_dynamic_lds_size
    .group_segment_fixed_size: 0
    .kernarg_segment_align: 8
    .kernarg_segment_size: 408
    .language:       OpenCL C
    .language_version:
      - 2
      - 0
    .max_flat_workgroup_size: 512
    .name:           _Z3fwd4Args
    .private_segment_fixed_size: 0
    .sgpr_count:     104
    .sgpr_spill_count: 97
    .symbol:         _Z3fwd4Args.kd
    .uniform_work_group_size: 1
    .uses_dynamic_stack: false
    .vgpr_count:     240
    .vgpr_spill_count: 0
    .wavefront_size: 64
